# P0: each thread's rope-table position (cold dword) loaded at kernel start into a spare register instead of right before the sin/cos code at the end of P0
# speedup vs baseline: 1.0023x; 1.0001x over previous
; #define LAS __attribute__((address_space(3)))
; __device__ __forceinline__ unsigned xb_xcc_id() { return (unsigned)__builtin_amdgcn_s_getreg((3 << 11) | 20) & 0xFu; }
; #define TBEG(bit) do { if (((PROBE_SPIN) >> (bit)) & 1) tst_ = __builtin_amdgcn_s_memrealtime(); } while (0)
; __global__ void __launch_bounds__(NWAVES * 64, 2) fwd_kernel(Args args) {
;     ...
;     f16_t* Win_t = (f16_t*)(ws + WS_WIN); f16_t* Wout_t = (f16_t*)(ws + WS_WOUT); f16_t* Wup_t = (f16_t*)(ws + WS_WUP); f16_t* Wdn_t = (f16_t*)(ws + WS_WDN);
;     f16_t* Wpg_t = (f16_t*)(ws + WS_WPG); f16_t* Wpp_t = (f16_t*)(ws + WS_WPP); f16_t* CW16 = (f16_t*)(ws + WS_CW); float* rinv0 = (float*)(ws + WS_CW + 64 * 1024);
;     f16_t* ropec = (f16_t*)(ws + WS_ROPE); f16_t* ropes = (f16_t*)(ws + WS_ROPE + 512 * 1024);
;     f16_t* XN = (f16_t*)(ws + WS_XN); f16_t* PP = (f16_t*)(ws + WS_PP); f16_t* HID = (f16_t*)(ws + WS_HID);
;     f16_t* P16 = (f16_t*)(ws + WS_P16); f16_t* Ub = (f16_t*)(ws + WS_U); f16_t* Kb = (f16_t*)(ws + WS_K); f16_t* Vb = (f16_t*)(ws + WS_V); f16_t* MIX = (f16_t*)(ws + WS_MIX);
;     float* kms = (float*)(ws + WS_CTL + CTL_KMS); float* rss1 = (float*)(ws + WS_CTL + CTL_RSS1); float* rss2 = (float*)(ws + WS_CTL + CTL_RSS2); float* rss3 = (float*)(ws + WS_CTL + CTL_RSS3);
;     for (int u = tid; u < (LDS_BYTES - LDSCTL_OFF) / 4; u += NWAVES * 64) ((LAS unsigned*)(lds + LDSCTL_OFF))[u] = 0u;
;     __syncthreads();
;     XcdBarrier bar; bar.bar = (unsigned*)(ws + WS_CTL + CTL_BAR); bar.x = 0; bar.st = nullptr;
;     if (args.ph_hi - args.ph_lo > 1) bar = xcd_barrier_post((unsigned*)(ws + WS_CTL + CTL_BAR), (volatile LAS unsigned*)(lds + MISC_OFF) + 8);
;     if (args.ph_hi - args.ph_lo > 1 && tid == 0) __hip_atomic_store((unsigned*)(ws + WS_CTL + CTL_XCCTAB) + (bx & 255), 1u + xb_xcc_id(), __ATOMIC_RELAXED, __HIP_MEMORY_SCOPE_AGENT);
;     const int lo = args.ph_lo, hi = args.ph_hi;
;     ...
;     unsigned long long tacc_ = 0ull, tst_ = 0ull;
;     ...
;     const bool dry = args.dry != 0;
;     float* dmy_out = (float*)(ws + WS_DUMMY); float* dmy_rss = (float*)(ws + WS_DUMMY + 64 * MiB); f16_t* dmy_mix = (f16_t*)(ws + WS_DUMMY);
;     const int gw = vcu * NWAVES + wave, NGW = G * NWAVES;
;     TBEG(0);
;     if (IN(0)) {
;         const int lane = tid & 63;
;         if (G == 256) convert_weights(args, 0, WI_P1 + WI_OUT, wave * G + vcu, NGW, lane); else convert_weights(args, 0, WI_ALL, gw, NGW, lane);
.LBB0_17:
	s_or_b64 exec, exec, s[0:1]
	v_lshl_add_u32 v2, s85, 9, v0
	v_ashrrev_i32_e32 v2, 3, v2
	v_lshlrev_b32_e32 v2, 2, v2
	global_load_dword v253, v2, s[40:41]
	s_add_u32 s0, s22, 0x600000
	s_addc_u32 s1, s23, 0
	s_add_u32 s96, s22, 0x1300000
	s_addc_u32 s97, s23, 0
	s_add_u32 s70, s22, 0x1b00000
	s_addc_u32 s71, s23, 0
	s_add_u32 s86, s22, 0x1b90000
	s_addc_u32 s87, s23, 0
	s_add_u32 s90, s22, 0x100000
	v_writelane_b32 v254, s0, 18
	s_addc_u32 s91, s23, 0
	s_nop 0
	v_writelane_b32 v254, s1, 19
	s_add_u32 s0, s22, 0x800000
	s_addc_u32 s1, s23, 0
	s_add_u32 s94, s22, 0x1900000
	s_addc_u32 s95, s23, 0
	s_add_u32 s56, s22, 0x1b80000
	s_addc_u32 s57, s23, 0
	v_writelane_b32 v254, s0, 20
	s_add_u32 s74, s22, 0x1d00000
	s_addc_u32 s75, s23, 0
	v_writelane_b32 v254, s1, 21
	s_lshr_b32 s0, s11, 6
	s_lshl_b32 s26, s85, 3
	s_add_i32 s34, s26, s0
	s_lshl_b32 s68, s69, 3
	s_cmp_lt_i32 s76, 1
	v_writelane_b32 v254, s0, 22
	s_cselect_b64 s[0:1], -1, 0
	s_cmp_gt_i32 s77, 0
	s_cselect_b64 s[2:3], -1, 0
	s_and_b64 s[0:1], s[0:1], s[2:3]
	s_andn2_b64 vcc, exec, s[0:1]
	v_writelane_b32 v254, s56, 23
	s_nop 1
	v_writelane_b32 v254, s57, 24
	s_cbranch_vccnz .LBB0_162
	s_cmpk_lg_i32 s69, 0x100
	s_cselect_b64 s[6:7], -1, 0
	v_and_b32_e32 v134, 63, v0
	s_mov_b64 s[2:3], -1
	s_and_b64 vcc, exec, s[6:7]
	s_cbranch_vccz .LBB0_71
	s_cmpk_gt_i32 s34, 0xcff
	s_cbranch_scc1 .LBB0_70
	s_cmpk_lt_i32 s34, 0x280
	s_mov_b32 s28, 0
	s_cbranch_scc1 .LBB0_26
	s_cmpk_gt_u32 s34, 0x2bf
	s_cbranch_scc0 .LBB0_27
	s_cmpk_gt_u32 s34, 0x3bf
	s_cbranch_scc0 .LBB0_28
	s_cmpk_gt_u32 s34, 0x93f
	s_cbranch_scc0 .LBB0_29
	s_cmpk_gt_u32 s34, 0xbff
	s_cbranch_scc0 .LBB0_30
	v_readlane_b32 s52, v254, 2
	v_readlane_b32 s62, v254, 12
	v_readlane_b32 s63, v254, 13
	v_readlane_b32 s64, v254, 14
	v_readlane_b32 s65, v254, 15
	s_add_i32 s16, s34, 0xfffff400
	s_mov_b64 s[2:3], 0
	v_readlane_b32 s53, v254, 3
	v_readlane_b32 s54, v254, 4
	v_readlane_b32 s55, v254, 5
	v_readlane_b32 s56, v254, 6
	v_readlane_b32 s57, v254, 7
	v_readlane_b32 s58, v254, 8
	v_readlane_b32 s59, v254, 9
	v_readlane_b32 s60, v254, 10
	v_readlane_b32 s61, v254, 11
	v_readlane_b32 s66, v254, 16
	v_readlane_b32 s67, v254, 17
	s_mov_b64 s[8:9], s[62:63]
	s_mov_b64 s[12:13], s[64:65]
	s_branch .LBB0_31

; __global__ void __launch_bounds__(NWAVES * 64, 2) fwd_kernel(Args args) {
;     ...
;         for (int i = vcu * 512 + tid; i < M * 8; i += G * 512) {
;             const int m = i >> 3, f = i & 7;
;             const float invf = (f == 0) ? 1.0f : (f == 1) ? 0.1939227432012558f : (f == 2) ? 0.03760603070259094f : (f == 3) ? 0.007292664609849453f : (f == 4) ? 0.0014142135623842478f
;                              : (f == 5) ? 0.00027424818836152554f : (f == 6) ? 5.318296098266728e-05f : 1.0313386155758053e-05f;
;             const float ang = (float)positions[m] * invf;
;             float sn, cs; sincos_d((double)ang, sn, cs);
;             ropec[i] = (f16_t)cs; ropes[i] = (f16_t)sn;
.LBB0_158:
	s_or_b64 exec, exec, s[2:3]
	v_ashrrev_i32_e32 v30, 3, v66
	v_ashrrev_i32_e32 v31, 31, v30
	v_lshl_add_u64 v[30:31], v[30:31], 2, s[40:41]
	v_mov_b32_e32 v29, v253
	s_movk_i32 s2, 0xffe0
	s_waitcnt vmcnt(0)
	v_cvt_f32_i32_e32 v29, v29
	v_mul_f32_e32 v28, v28, v29
	v_cvt_f64_f32_e32 v[28:29], v28
	v_mul_f64 v[30:31], v[28:29], s[16:17]
	v_rndne_f64_e32 v[30:31], v[30:31]
	v_fmac_f64_e32 v[28:29], s[18:19], v[30:31]
	v_ldexp_f64 v[32:33], v[30:31], s2
	v_fmac_f64_e32 v[28:29], s[20:21], v[30:31]
	v_floor_f64_e32 v[32:33], v[32:33]
	v_mul_f64 v[38:39], v[28:29], v[28:29]
	v_fmac_f64_e32 v[30:31], 0xc1f00000, v[32:33]
	v_fma_f64 v[32:33], s[36:37], v[38:39], v[4:5]
	v_fma_f64 v[40:41], s[46:47], v[38:39], v[16:17]
	v_cvt_u32_f64_e32 v42, v[30:31]
	v_fma_f64 v[30:31], v[38:39], v[32:33], v[6:7]
	v_fma_f64 v[40:41], v[38:39], v[40:41], v[18:19]
	v_fma_f64 v[30:31], v[38:39], v[30:31], v[8:9]
	v_fma_f64 v[40:41], v[38:39], v[40:41], v[20:21]
	v_fma_f64 v[30:31], v[38:39], v[30:31], v[10:11]
	v_fma_f64 v[40:41], v[38:39], v[40:41], v[22:23]
	v_fma_f64 v[30:31], v[38:39], v[30:31], v[12:13]
	v_fma_f64 v[40:41], v[38:39], v[40:41], v[24:25]
	v_fma_f64 v[30:31], v[38:39], v[30:31], v[14:15]
	v_fma_f64 v[40:41], v[38:39], v[40:41], v[26:27]
	v_and_b32_e32 v32, 3, v42
	v_mul_f64 v[30:31], v[38:39], v[30:31]
	v_fma_f64 v[40:41], v[38:39], v[40:41], -0.5
	v_fmac_f64_e32 v[28:29], v[28:29], v[30:31]
	v_fma_f64 v[30:31], v[38:39], v[40:41], 1.0
	v_cmp_lt_i32_e32 vcc, 0, v32
	s_and_saveexec_b64 s[24:25], vcc
	s_cbranch_execz .LBB0_139
	v_cmp_eq_u32_e32 vcc, 1, v32
	v_cmp_eq_u32_e64 s[2:3], 2, v32
	v_cmp_ne_u32_e64 s[4:5], 1, v32
	v_xor_b32_e32 v33, 0x80000000, v29
	v_mov_b32_e32 v32, v28
	s_and_saveexec_b64 s[26:27], s[4:5]
	s_xor_b64 s[4:5], exec, s[26:27]
	s_cbranch_execz .LBB0_138
	v_xor_b32_e32 v32, 0x80000000, v31
	v_cndmask_b32_e64 v33, v29, v32, s[2:3]
	v_cndmask_b32_e64 v32, v28, v30, s[2:3]
	s_branch .LBB0_138
